# grid barrier: two staggered polls of the top counter in flight, no sleep (on top of early write-back by arrivers 0/16)
# baseline (speedup 1.0000x reference)
; __device__ __forceinline__ void grid_barrier(unsigned* bar, unsigned k, unsigned info, int swave) {
;     ...
;       while (__hip_atomic_load(bar + 64 * 16, __ATOMIC_RELAXED, __HIP_MEMORY_SCOPE_AGENT) < k * nxcc) __builtin_amdgcn_s_sleep(1);
;       __builtin_amdgcn_fence(__ATOMIC_ACQUIRE, "agent");
;       asm volatile("s_waitcnt vmcnt(0)" ::: "memory");
.LBB0_33:
	s_or_b64 exec, exec, s[2:3]
	global_load_dword v0, v3, s[86:87] sc1
	v_readlane_b32 s2, v248, 61
	v_readlane_b32 s3, v247, 43
	s_mul_i32 s2, s3, s2
	s_sleep 12
	global_load_dword v1, v3, s[86:87] sc1
.LBB0_34:
	s_waitcnt vmcnt(1)
	v_cmp_gt_u32_e32 vcc, s2, v0
	s_cbranch_vccz .LBB0_35
	global_load_dword v0, v3, s[86:87] sc1
	s_waitcnt vmcnt(1)
	v_cmp_gt_u32_e32 vcc, s2, v1
	s_cbranch_vccz .LBB0_35
	global_load_dword v1, v3, s[86:87] sc1
	s_branch .LBB0_34
